# stack25 + L2 touch loads for the 15 later residual segments at the start of the P10 EpiResid epilogue
# baseline (speedup 1.0000x reference)
.LBB0_1330:
	s_andn2_b64 vcc, exec, s[18:19]
	s_cbranch_vccnz .LBB0_1332
	v_lshl_or_b32 v146, s11, 8, v149
	v_ashrrev_i32_e32 v147, 31, v146
	v_lshl_or_b32 v144, s52, 8, v150
	v_ashrrev_i32_e32 v145, 31, v144
	v_lshlrev_b64 v[154:155], 13, v[146:147]
	v_lshl_add_u64 v[154:155], s[12:13], 0, v[154:155]
	v_lshlrev_b64 v[144:145], 2, v[144:145]
	v_lshl_add_u64 v[162:163], v[154:155], 0, v[144:145]
	global_load_dwordx4 v[154:157], v[162:163], off
	global_load_dwordx4 v[158:161], v[162:163], off offset:16
	global_load_dword v231, v[162:163], off offset:512
	s_mov_b64 s[98:99], 0x20000
	v_lshl_add_u64 v[228:229], v[162:163], 0, s[98:99]
	global_load_dword v231, v[228:229], off
	global_load_dword v231, v[228:229], off offset:512
	s_mov_b64 s[98:99], 0x40000
	v_lshl_add_u64 v[228:229], v[162:163], 0, s[98:99]
	global_load_dword v231, v[228:229], off
	global_load_dword v231, v[228:229], off offset:512
	s_mov_b64 s[98:99], 0x60000
	v_lshl_add_u64 v[228:229], v[162:163], 0, s[98:99]
	global_load_dword v231, v[228:229], off
	global_load_dword v231, v[228:229], off offset:512
	s_mov_b64 s[98:99], 0x100000
	v_lshl_add_u64 v[228:229], v[162:163], 0, s[98:99]
	global_load_dword v231, v[228:229], off
	global_load_dword v231, v[228:229], off offset:512
	s_mov_b64 s[98:99], 0x120000
	v_lshl_add_u64 v[228:229], v[162:163], 0, s[98:99]
	global_load_dword v231, v[228:229], off
	global_load_dword v231, v[228:229], off offset:512
	s_mov_b64 s[98:99], 0x140000
	v_lshl_add_u64 v[228:229], v[162:163], 0, s[98:99]
	global_load_dword v231, v[228:229], off
	global_load_dword v231, v[228:229], off offset:512
	s_mov_b64 s[98:99], 0x160000
	v_lshl_add_u64 v[228:229], v[162:163], 0, s[98:99]
	global_load_dword v231, v[228:229], off
	global_load_dword v231, v[228:229], off offset:512
	s_waitcnt vmcnt(0)
	v_pk_fma_f32 v[126:127], v[126:127], 0.5, v[156:157] op_sel_hi:[1,0,1]
	v_pk_fma_f32 v[124:125], v[124:125], 0.5, v[154:155] op_sel_hi:[1,0,1]
	v_pk_fma_f32 v[122:123], v[122:123], 0.5, v[160:161] op_sel_hi:[1,0,1]
	v_pk_fma_f32 v[120:121], v[120:121], 0.5, v[158:159] op_sel_hi:[1,0,1]
	global_store_dwordx4 v[162:163], v[124:127], off
	global_store_dwordx4 v[162:163], v[120:123], off offset:16
	global_load_dwordx4 v[120:123], v[162:163], off offset:512
	s_nop 0
	global_load_dwordx4 v[124:127], v[162:163], off offset:528
	s_waitcnt vmcnt(1)
	v_pk_fma_f32 v[118:119], v[118:119], 0.5, v[122:123] op_sel_hi:[1,0,1]
	s_waitcnt vmcnt(0)
	v_pk_fma_f32 v[112:113], v[112:113], 0.5, v[124:125] op_sel_hi:[1,0,1]
	v_pk_fma_f32 v[116:117], v[116:117], 0.5, v[120:121] op_sel_hi:[1,0,1]
	v_pk_fma_f32 v[114:115], v[114:115], 0.5, v[126:127] op_sel_hi:[1,0,1]
	global_store_dwordx4 v[162:163], v[116:119], off offset:512
	global_store_dwordx4 v[162:163], v[112:115], off offset:528
	s_nop 1
	v_or_b32_e32 v112, 16, v146
	v_ashrrev_i32_e32 v113, 31, v112
	v_lshlrev_b64 v[112:113], 13, v[112:113]
	v_lshl_add_u64 v[112:113], s[12:13], 0, v[112:113]
	v_lshl_add_u64 v[120:121], v[112:113], 0, v[144:145]
	global_load_dwordx4 v[112:115], v[120:121], off
	global_load_dwordx4 v[116:119], v[120:121], off offset:16
	s_waitcnt vmcnt(1)
	v_pk_fma_f32 v[110:111], v[110:111], 0.5, v[114:115] op_sel_hi:[1,0,1]
	v_pk_fma_f32 v[108:109], v[108:109], 0.5, v[112:113] op_sel_hi:[1,0,1]
	s_waitcnt vmcnt(0)
	v_pk_fma_f32 v[106:107], v[106:107], 0.5, v[118:119] op_sel_hi:[1,0,1]
	v_pk_fma_f32 v[104:105], v[104:105], 0.5, v[116:117] op_sel_hi:[1,0,1]
	global_store_dwordx4 v[120:121], v[108:111], off
	global_store_dwordx4 v[120:121], v[104:107], off offset:16
	global_load_dwordx4 v[104:107], v[120:121], off offset:512
	s_nop 0
	global_load_dwordx4 v[108:111], v[120:121], off offset:528
	s_waitcnt vmcnt(1)
	v_pk_fma_f32 v[102:103], v[102:103], 0.5, v[106:107] op_sel_hi:[1,0,1]
	s_waitcnt vmcnt(0)
	v_pk_fma_f32 v[96:97], v[96:97], 0.5, v[108:109] op_sel_hi:[1,0,1]
	v_pk_fma_f32 v[100:101], v[100:101], 0.5, v[104:105] op_sel_hi:[1,0,1]
	v_pk_fma_f32 v[98:99], v[98:99], 0.5, v[110:111] op_sel_hi:[1,0,1]
	global_store_dwordx4 v[120:121], v[100:103], off offset:512
	global_store_dwordx4 v[120:121], v[96:99], off offset:528
	s_nop 1
	v_or_b32_e32 v96, 32, v146
	v_ashrrev_i32_e32 v97, 31, v96
	v_lshlrev_b64 v[96:97], 13, v[96:97]
	v_lshl_add_u64 v[96:97], s[12:13], 0, v[96:97]
	v_lshl_add_u64 v[104:105], v[96:97], 0, v[144:145]
	global_load_dwordx4 v[96:99], v[104:105], off
	global_load_dwordx4 v[100:103], v[104:105], off offset:16
	s_waitcnt vmcnt(1)
	v_pk_fma_f32 v[94:95], v[94:95], 0.5, v[98:99] op_sel_hi:[1,0,1]
	v_pk_fma_f32 v[92:93], v[92:93], 0.5, v[96:97] op_sel_hi:[1,0,1]
	s_waitcnt vmcnt(0)
	v_pk_fma_f32 v[90:91], v[90:91], 0.5, v[102:103] op_sel_hi:[1,0,1]
	v_pk_fma_f32 v[88:89], v[88:89], 0.5, v[100:101] op_sel_hi:[1,0,1]
	global_store_dwordx4 v[104:105], v[92:95], off
	global_store_dwordx4 v[104:105], v[88:91], off offset:16
	global_load_dwordx4 v[88:91], v[104:105], off offset:512
	s_nop 0
	global_load_dwordx4 v[92:95], v[104:105], off offset:528
	s_waitcnt vmcnt(1)
	v_pk_fma_f32 v[86:87], v[86:87], 0.5, v[90:91] op_sel_hi:[1,0,1]
	s_waitcnt vmcnt(0)
	v_pk_fma_f32 v[80:81], v[80:81], 0.5, v[92:93] op_sel_hi:[1,0,1]
	v_pk_fma_f32 v[84:85], v[84:85], 0.5, v[88:89] op_sel_hi:[1,0,1]
	v_pk_fma_f32 v[82:83], v[82:83], 0.5, v[94:95] op_sel_hi:[1,0,1]
	global_store_dwordx4 v[104:105], v[84:87], off offset:512
	global_store_dwordx4 v[104:105], v[80:83], off offset:528
	s_nop 1
	v_or_b32_e32 v80, 48, v146
	v_ashrrev_i32_e32 v81, 31, v80
	v_lshlrev_b64 v[80:81], 13, v[80:81]
	v_lshl_add_u64 v[80:81], s[12:13], 0, v[80:81]
	v_lshl_add_u64 v[88:89], v[80:81], 0, v[144:145]
	global_load_dwordx4 v[80:83], v[88:89], off
	global_load_dwordx4 v[84:87], v[88:89], off offset:16
	s_waitcnt vmcnt(1)
	v_pk_fma_f32 v[78:79], v[78:79], 0.5, v[82:83] op_sel_hi:[1,0,1]
	v_pk_fma_f32 v[76:77], v[76:77], 0.5, v[80:81] op_sel_hi:[1,0,1]
	s_waitcnt vmcnt(0)
	v_pk_fma_f32 v[74:75], v[74:75], 0.5, v[86:87] op_sel_hi:[1,0,1]
	v_pk_fma_f32 v[72:73], v[72:73], 0.5, v[84:85] op_sel_hi:[1,0,1]
	global_store_dwordx4 v[88:89], v[76:79], off
	global_store_dwordx4 v[88:89], v[72:75], off offset:16
	global_load_dwordx4 v[72:75], v[88:89], off offset:512
	s_nop 0
	global_load_dwordx4 v[76:79], v[88:89], off offset:528
	s_waitcnt vmcnt(1)
	v_pk_fma_f32 v[70:71], v[70:71], 0.5, v[74:75] op_sel_hi:[1,0,1]
	s_waitcnt vmcnt(0)
	v_pk_fma_f32 v[64:65], v[64:65], 0.5, v[76:77] op_sel_hi:[1,0,1]
	v_pk_fma_f32 v[68:69], v[68:69], 0.5, v[72:73] op_sel_hi:[1,0,1]
	v_pk_fma_f32 v[66:67], v[66:67], 0.5, v[78:79] op_sel_hi:[1,0,1]
	global_store_dwordx4 v[88:89], v[68:71], off offset:512
	global_store_dwordx4 v[88:89], v[64:67], off offset:528
	s_nop 1
	v_or_b32_e32 v64, 0x80, v146
	v_ashrrev_i32_e32 v65, 31, v64
	v_lshlrev_b64 v[64:65], 13, v[64:65]
	v_lshl_add_u64 v[64:65], s[12:13], 0, v[64:65]
	v_lshl_add_u64 v[72:73], v[64:65], 0, v[144:145]
	global_load_dwordx4 v[64:67], v[72:73], off
	global_load_dwordx4 v[68:71], v[72:73], off offset:16
	s_waitcnt vmcnt(1)
	v_pk_fma_f32 v[62:63], v[62:63], 0.5, v[66:67] op_sel_hi:[1,0,1]
	v_pk_fma_f32 v[60:61], v[60:61], 0.5, v[64:65] op_sel_hi:[1,0,1]
	s_waitcnt vmcnt(0)
	v_pk_fma_f32 v[58:59], v[58:59], 0.5, v[70:71] op_sel_hi:[1,0,1]
	v_pk_fma_f32 v[56:57], v[56:57], 0.5, v[68:69] op_sel_hi:[1,0,1]
	global_store_dwordx4 v[72:73], v[60:63], off
	global_store_dwordx4 v[72:73], v[56:59], off offset:16
	global_load_dwordx4 v[56:59], v[72:73], off offset:512
	s_nop 0
	global_load_dwordx4 v[60:63], v[72:73], off offset:528
	s_waitcnt vmcnt(1)
	v_pk_fma_f32 v[54:55], v[54:55], 0.5, v[58:59] op_sel_hi:[1,0,1]
	s_waitcnt vmcnt(0)
	v_pk_fma_f32 v[48:49], v[48:49], 0.5, v[60:61] op_sel_hi:[1,0,1]
	v_pk_fma_f32 v[52:53], v[52:53], 0.5, v[56:57] op_sel_hi:[1,0,1]
	v_pk_fma_f32 v[50:51], v[50:51], 0.5, v[62:63] op_sel_hi:[1,0,1]
	global_store_dwordx4 v[72:73], v[52:55], off offset:512
	global_store_dwordx4 v[72:73], v[48:51], off offset:528
	s_nop 1
	v_or_b32_e32 v48, 0x90, v146
	v_ashrrev_i32_e32 v49, 31, v48
	v_lshlrev_b64 v[48:49], 13, v[48:49]
	v_lshl_add_u64 v[48:49], s[12:13], 0, v[48:49]
	v_lshl_add_u64 v[56:57], v[48:49], 0, v[144:145]
	global_load_dwordx4 v[48:51], v[56:57], off
	global_load_dwordx4 v[52:55], v[56:57], off offset:16
	s_waitcnt vmcnt(1)
	v_pk_fma_f32 v[46:47], v[46:47], 0.5, v[50:51] op_sel_hi:[1,0,1]
	v_pk_fma_f32 v[44:45], v[44:45], 0.5, v[48:49] op_sel_hi:[1,0,1]
	s_waitcnt vmcnt(0)
	v_pk_fma_f32 v[42:43], v[42:43], 0.5, v[54:55] op_sel_hi:[1,0,1]
	v_pk_fma_f32 v[40:41], v[40:41], 0.5, v[52:53] op_sel_hi:[1,0,1]
	global_store_dwordx4 v[56:57], v[44:47], off
	global_store_dwordx4 v[56:57], v[40:43], off offset:16
	global_load_dwordx4 v[40:43], v[56:57], off offset:512
	s_nop 0
	global_load_dwordx4 v[44:47], v[56:57], off offset:528
	s_waitcnt vmcnt(1)
	v_pk_fma_f32 v[38:39], v[38:39], 0.5, v[42:43] op_sel_hi:[1,0,1]
	s_waitcnt vmcnt(0)
	v_pk_fma_f32 v[32:33], v[32:33], 0.5, v[44:45] op_sel_hi:[1,0,1]
	v_pk_fma_f32 v[36:37], v[36:37], 0.5, v[40:41] op_sel_hi:[1,0,1]
	v_pk_fma_f32 v[34:35], v[34:35], 0.5, v[46:47] op_sel_hi:[1,0,1]
	global_store_dwordx4 v[56:57], v[36:39], off offset:512
	global_store_dwordx4 v[56:57], v[32:35], off offset:528
	s_nop 1
	v_or_b32_e32 v32, 0xa0, v146
	v_ashrrev_i32_e32 v33, 31, v32
	v_lshlrev_b64 v[32:33], 13, v[32:33]
	v_lshl_add_u64 v[32:33], s[12:13], 0, v[32:33]
	v_lshl_add_u64 v[40:41], v[32:33], 0, v[144:145]
	global_load_dwordx4 v[32:35], v[40:41], off
	global_load_dwordx4 v[36:39], v[40:41], off offset:16
	s_waitcnt vmcnt(1)
	v_pk_fma_f32 v[30:31], v[30:31], 0.5, v[34:35] op_sel_hi:[1,0,1]
	v_pk_fma_f32 v[28:29], v[28:29], 0.5, v[32:33] op_sel_hi:[1,0,1]
	s_waitcnt vmcnt(0)
	v_pk_fma_f32 v[26:27], v[26:27], 0.5, v[38:39] op_sel_hi:[1,0,1]
	v_pk_fma_f32 v[24:25], v[24:25], 0.5, v[36:37] op_sel_hi:[1,0,1]
	global_store_dwordx4 v[40:41], v[28:31], off
	global_store_dwordx4 v[40:41], v[24:27], off offset:16
	global_load_dwordx4 v[24:27], v[40:41], off offset:512
	s_nop 0
	global_load_dwordx4 v[28:31], v[40:41], off offset:528
	s_waitcnt vmcnt(1)
	v_pk_fma_f32 v[22:23], v[22:23], 0.5, v[26:27] op_sel_hi:[1,0,1]
	s_waitcnt vmcnt(0)
	v_pk_fma_f32 v[16:17], v[16:17], 0.5, v[28:29] op_sel_hi:[1,0,1]
	v_pk_fma_f32 v[20:21], v[20:21], 0.5, v[24:25] op_sel_hi:[1,0,1]
	v_pk_fma_f32 v[18:19], v[18:19], 0.5, v[30:31] op_sel_hi:[1,0,1]
	global_store_dwordx4 v[40:41], v[20:23], off offset:512
	global_store_dwordx4 v[40:41], v[16:19], off offset:528
	s_nop 1
	v_or_b32_e32 v16, 0xb0, v146
	v_ashrrev_i32_e32 v17, 31, v16
	v_lshlrev_b64 v[16:17], 13, v[16:17]
	v_lshl_add_u64 v[16:17], s[12:13], 0, v[16:17]
	v_lshl_add_u64 v[16:17], v[16:17], 0, v[144:145]
	global_load_dwordx4 v[18:21], v[16:17], off
	global_load_dwordx4 v[22:25], v[16:17], off offset:16
	s_waitcnt vmcnt(1)
	v_pk_fma_f32 v[14:15], v[14:15], 0.5, v[20:21] op_sel_hi:[1,0,1]
	v_pk_fma_f32 v[12:13], v[12:13], 0.5, v[18:19] op_sel_hi:[1,0,1]
	s_waitcnt vmcnt(0)
	v_pk_fma_f32 v[10:11], v[10:11], 0.5, v[24:25] op_sel_hi:[1,0,1]
	v_pk_fma_f32 v[8:9], v[8:9], 0.5, v[22:23] op_sel_hi:[1,0,1]
	global_store_dwordx4 v[16:17], v[12:15], off
	global_store_dwordx4 v[16:17], v[8:11], off offset:16
	global_load_dwordx4 v[8:11], v[16:17], off offset:512
	s_nop 0
	global_load_dwordx4 v[12:15], v[16:17], off offset:528
	s_waitcnt vmcnt(1)
	v_pk_fma_f32 v[6:7], v[6:7], 0.5, v[10:11] op_sel_hi:[1,0,1]
	v_pk_fma_f32 v[4:5], v[4:5], 0.5, v[8:9] op_sel_hi:[1,0,1]
	s_waitcnt vmcnt(0)
	v_pk_fma_f32 v[2:3], v[2:3], 0.5, v[14:15] op_sel_hi:[1,0,1]
	v_pk_fma_f32 v[0:1], v[0:1], 0.5, v[12:13] op_sel_hi:[1,0,1]
	global_store_dwordx4 v[16:17], v[4:7], off offset:512
	global_store_dwordx4 v[16:17], v[0:3], off offset:528

	.amdhsa_kernel _Z8mega_fwd4Args
		.amdhsa_group_segment_fixed_size 0
		.amdhsa_private_segment_fixed_size 0
		.amdhsa_kernarg_size 464
		.amdhsa_user_sgpr_count 2
		.amdhsa_user_sgpr_dispatch_ptr 0
		.amdhsa_user_sgpr_queue_ptr 0
		.amdhsa_user_sgpr_kernarg_segment_ptr 1
		.amdhsa_user_sgpr_dispatch_id 0
		.amdhsa_user_sgpr_kernarg_preload_length 0
		.amdhsa_user_sgpr_kernarg_preload_offset 0
		.amdhsa_user_sgpr_private_segment_size 0
		.amdhsa_uses_dynamic_stack 0
		.amdhsa_enable_private_segment 0
		.amdhsa_system_sgpr_workgroup_id_x 1
		.amdhsa_system_sgpr_workgroup_id_y 0
		.amdhsa_system_sgpr_workgroup_id_z 0
		.amdhsa_system_sgpr_workgroup_info 0
		.amdhsa_system_vgpr_workitem_id 2
		.amdhsa_next_free_vgpr 232
		.amdhsa_next_free_sgpr 100
		.amdhsa_accum_offset 232
		.amdhsa_reserve_vcc 1
		.amdhsa_float_round_mode_32 0
		.amdhsa_float_round_mode_16_64 0
		.amdhsa_float_denorm_mode_32 3
		.amdhsa_float_denorm_mode_16_64 3
		.amdhsa_dx10_clamp 1
		.amdhsa_ieee_mode 1
		.amdhsa_fp16_overflow 0
		.amdhsa_tg_split 0
		.amdhsa_exception_fp_ieee_invalid_op 0
		.amdhsa_exception_fp_denorm_src 0
		.amdhsa_exception_fp_ieee_div_zero 0
		.amdhsa_exception_fp_ieee_overflow 0
		.amdhsa_exception_fp_ieee_underflow 0
		.amdhsa_exception_fp_ieee_inexact 0
		.amdhsa_exception_int_div_zero 0
	.end_amdhsa_kernel

amdhsa.kernels:
  - .agpr_count:     0
    .args:
      - .offset:         0
        .size:           208
        .value_kind:     by_value
      - .offset:         208
        .size:           4
        .value_kind:     hidden_block_count_x
      - .offset:         212
        .size:           4
        .value_kind:     hidden_block_count_y
      - .offset:         216
        .size:           4
        .value_kind:     hidden_block_count_z
      - .offset:         220
        .size:           2
        .value_kind:     hidden_group_size_x
      - .offset:         222
        .size:           2
        .value_kind:     hidden_group_size_y
      - .offset:         224
        .size:           2
        .value_kind:     hidden_group_size_z
      - .offset:         226
        .size:           2
        .value_kind:     hidden_remainder_x
      - .offset:         228
        .size:           2
        .value_kind:     hidden_remainder_y
      - .offset:         230
        .size:           2
        .value_kind:     hidden_remainder_z
      - .offset:         248
        .size:           8
        .value_kind:     hidden_global_offset_x
      - .offset:         256
        .size:           8
        .value_kind:     hidden_global_offset_y
      - .offset:         264
        .size:           8
        .value_kind:     hidden_global_offset_z
      - .offset:         272
        .size:           2
        .value_kind:     hidden_grid_dims
      - .offset:         296
        .size:           8
        .value_kind:     hidden_multigrid_sync_arg
      - .offset:         328
        .size:           4
        .value_kind:     hidden_dynamic_lds_size
    .group_segment_fixed_size: 0
    .kernarg_segment_align: 8
    .kernarg_segment_size: 464
    .language:       OpenCL C
    .language_version:
      - 2
      - 0
    .max_flat_workgroup_size: 512
    .name:           _Z8mega_fwd4Args
    .private_segment_fixed_size: 0
    .sgpr_count:     106
    .sgpr_spill_count: 8
    .symbol:         _Z8mega_fwd4Args.kd
    .uniform_work_group_size: 1
    .uses_dynamic_stack: false
    .vgpr_count:     232
    .vgpr_spill_count: 0
    .wavefront_size: 64
